# P2 tail: sample_gemm32 rewritten (weights by LDS-DMA into 3 resident K-chunk buffers, 44 A-fragment loads in flight, exact counted waits)
# speedup vs baseline: 1.1070x; 1.0035x over previous
; #define SG_LA(c, d) do { _Pragma("unroll") for (int ks = 0; ks < 16; ++ks) d[ks] = *(const bf16x8*)(ap + (c) * CK + ks * 32); } while (0)
; #define SG_LB(c) do { _Pragma("unroll") for (int i = 0; i < 4; ++i) sb[i] = *(const u32x4*)(bp + (size_t)(8 * i) * DM + (c) * CK); } while (0)
; #define SG_SB(bufp) do { _Pragma("unroll") for (int i = 0; i < 4; ++i) *(LAS u32x4*)((bufp) + bw + (unsigned)(8 * i * BS * 2)) = sb[i]; } while (0)
; __device__ __forceinline__ void sample_gemm32(LAS unsigned char* lds, const bf16_t* A, const bf16_t* Bt, float* out, int ldo, int n0, int tid, int lane, int wave) {
;     constexpr int CK = 512, BS = CK + 8, BUFB = 32 * BS * 2, NC = DM / CK;
;     const int r = lane & 15, q8 = lane >> 4;
;     const bf16_t* ap = A + (size_t)(wave * 16 + r) * DM + q8 * 8;
;     const bf16_t* bp = Bt + (size_t)(tid >> 6) * DM + (tid & 63) * 8;
;     const unsigned bw = (unsigned)((tid >> 6) * BS + (tid & 63) * 8) * 2u;
;     f32x4 acc[2] = {{0.f, 0.f, 0.f, 0.f}, {0.f, 0.f, 0.f, 0.f}};
;     bf16x8 fa[16], fn[16]; u32x4 sb[4];
;     ...
;     SG_LB(0); SG_LA(0, fa);
;     SG_SB(lds);
;     SG_LB(1);
.LBB0_350:
	s_ashr_i32 s7, s6, 31
	s_lshl_b64 s[4:5], s[6:7], 17
	v_lshl_add_u64 v[178:179], v[164:165], 0, s[4:5]
	s_mul_i32 s10, s14, 0x410
	v_add_u32_e32 v238, 0x10400, v152
	v_mov_b32_e32 v228, 0
	v_mov_b32_e32 v229, 0
	v_mov_b32_e32 v230, 0
	v_mov_b32_e32 v231, 0
	v_mov_b32_e32 v232, 0
	v_mov_b32_e32 v233, 0
	v_mov_b32_e32 v234, 0
	v_mov_b32_e32 v235, 0
	s_mov_b64 s[4:5], 0x0
	s_add_i32 m0, s10, 0x0
	v_lshl_add_u64 v[236:237], v[178:179], 0, s[4:5]
	global_load_lds_dwordx4 v[236:237], off
	s_mov_b64 s[4:5], 0x8000
	s_add_i32 m0, s10, 0x2080
	v_lshl_add_u64 v[236:237], v[178:179], 0, s[4:5]
	global_load_lds_dwordx4 v[236:237], off
	s_mov_b64 s[4:5], 0x10000
	s_add_i32 m0, s10, 0x4100
	v_lshl_add_u64 v[236:237], v[178:179], 0, s[4:5]
	global_load_lds_dwordx4 v[236:237], off
	s_mov_b64 s[4:5], 0x18000
	s_add_i32 m0, s10, 0x6180
	v_lshl_add_u64 v[236:237], v[178:179], 0, s[4:5]
	global_load_lds_dwordx4 v[236:237], off
	global_load_dwordx4 v[0:3], v[166:167], off
	global_load_dwordx4 v[4:7], v[166:167], off offset:64
	global_load_dwordx4 v[8:11], v[166:167], off offset:128
	global_load_dwordx4 v[12:15], v[166:167], off offset:192
	global_load_dwordx4 v[16:19], v[166:167], off offset:256
	global_load_dwordx4 v[20:23], v[166:167], off offset:320
	global_load_dwordx4 v[24:27], v[166:167], off offset:384
	global_load_dwordx4 v[28:31], v[166:167], off offset:448
	global_load_dwordx4 v[32:35], v[166:167], off offset:512
	global_load_dwordx4 v[36:39], v[166:167], off offset:576
	global_load_dwordx4 v[40:43], v[166:167], off offset:640
	global_load_dwordx4 v[44:47], v[166:167], off offset:704
	global_load_dwordx4 v[48:51], v[166:167], off offset:768
	global_load_dwordx4 v[52:55], v[166:167], off offset:832
	global_load_dwordx4 v[56:59], v[166:167], off offset:896
	global_load_dwordx4 v[60:63], v[166:167], off offset:960
	s_mov_b64 s[4:5], 0x400
	s_add_i32 m0, s10, 0x8200
	v_lshl_add_u64 v[236:237], v[178:179], 0, s[4:5]
	global_load_lds_dwordx4 v[236:237], off
	s_mov_b64 s[4:5], 0x8400
	s_add_i32 m0, s10, 0xa280
	v_lshl_add_u64 v[236:237], v[178:179], 0, s[4:5]
	global_load_lds_dwordx4 v[236:237], off
	s_mov_b64 s[4:5], 0x10400
	s_add_i32 m0, s10, 0xc300
	v_lshl_add_u64 v[236:237], v[178:179], 0, s[4:5]
	global_load_lds_dwordx4 v[236:237], off
	s_mov_b64 s[4:5], 0x18400
	s_add_i32 m0, s10, 0xe380
	v_lshl_add_u64 v[236:237], v[178:179], 0, s[4:5]
	global_load_lds_dwordx4 v[236:237], off
	global_load_dwordx4 v[64:67], v[166:167], off offset:1024
	global_load_dwordx4 v[68:71], v[166:167], off offset:1088
	global_load_dwordx4 v[72:75], v[166:167], off offset:1152
	global_load_dwordx4 v[76:79], v[166:167], off offset:1216
	global_load_dwordx4 v[80:83], v[166:167], off offset:1280
	global_load_dwordx4 v[84:87], v[166:167], off offset:1344
	global_load_dwordx4 v[88:91], v[166:167], off offset:1408
	global_load_dwordx4 v[92:95], v[166:167], off offset:1472
	global_load_dwordx4 v[96:99], v[166:167], off offset:1536
	global_load_dwordx4 v[100:103], v[166:167], off offset:1600
	global_load_dwordx4 v[104:107], v[166:167], off offset:1664
	global_load_dwordx4 v[108:111], v[166:167], off offset:1728
	global_load_dwordx4 v[112:115], v[166:167], off offset:1792
	global_load_dwordx4 v[116:119], v[166:167], off offset:1856
	global_load_dwordx4 v[120:123], v[166:167], off offset:1920
	global_load_dwordx4 v[124:127], v[166:167], off offset:1984
	s_mov_b64 s[4:5], 0x800
	s_add_i32 m0, s10, 0x10400
	v_lshl_add_u64 v[236:237], v[178:179], 0, s[4:5]
	global_load_lds_dwordx4 v[236:237], off
	s_mov_b64 s[4:5], 0x8800
	s_add_i32 m0, s10, 0x12480
	v_lshl_add_u64 v[236:237], v[178:179], 0, s[4:5]
	global_load_lds_dwordx4 v[236:237], off
	s_mov_b64 s[4:5], 0x10800
	s_add_i32 m0, s10, 0x14500
	v_lshl_add_u64 v[236:237], v[178:179], 0, s[4:5]
	global_load_lds_dwordx4 v[236:237], off
	s_mov_b64 s[4:5], 0x18800
	s_add_i32 m0, s10, 0x16580
	v_lshl_add_u64 v[236:237], v[178:179], 0, s[4:5]
	global_load_lds_dwordx4 v[236:237], off
	global_load_dwordx4 v[128:131], v[166:167], off offset:2048
	global_load_dwordx4 v[132:135], v[166:167], off offset:2112
	global_load_dwordx4 v[136:139], v[166:167], off offset:2176
	global_load_dwordx4 v[140:143], v[166:167], off offset:2240
	global_load_dwordx4 v[144:147], v[166:167], off offset:2304
	global_load_dwordx4 v[148:151], v[166:167], off offset:2368
	global_load_dwordx4 v[204:207], v[166:167], off offset:2432
	global_load_dwordx4 v[208:211], v[166:167], off offset:2496
	global_load_dwordx4 v[212:215], v[166:167], off offset:2560
	global_load_dwordx4 v[216:219], v[166:167], off offset:2624
	global_load_dwordx4 v[220:223], v[166:167], off offset:2688
	global_load_dwordx4 v[224:227], v[166:167], off offset:2752
	s_waitcnt vmcnt(52)
	s_barrier
; #define LBAR() do { asm volatile("s_waitcnt lgkmcnt(0)" ::: "memory"); __builtin_amdgcn_s_barrier(); asm volatile("" ::: "memory"); } while (0)
; #define SG_LA(c, d) do { _Pragma("unroll") for (int ks = 0; ks < 16; ++ks) d[ks] = *(const bf16x8*)(ap + (c) * CK + ks * 32); } while (0)
; #define SG_LB(c) do { _Pragma("unroll") for (int i = 0; i < 4; ++i) sb[i] = *(const u32x4*)(bp + (size_t)(8 * i) * DM + (c) * CK); } while (0)
; #define SG_SB(bufp) do { _Pragma("unroll") for (int i = 0; i < 4; ++i) *(LAS u32x4*)((bufp) + bw + (unsigned)(8 * i * BS * 2)) = sb[i]; } while (0)
; __device__ __forceinline__ void sample_gemm32(LAS unsigned char* lds, const bf16_t* A, const bf16_t* Bt, float* out, int ldo, int n0, int tid, int lane, int wave) {
;     ...
; #pragma unroll 1
;     for (int c = 0; c < NC; c += 2) {
;         SG_LA(c + 1, fn);
;         SG_MM(fa, c);
;         SG_SB(lds + ((c + 1) & 1) * BUFB);
;         if (c + 2 < NC) SG_LB(c + 2);
;         LBAR();
;         if (c + 2 < NC) SG_LA(c + 2, fa);
	ds_read_b128 v[180:183], v152 offset:0
	ds_read_b128 v[184:187], v152 offset:16640
	ds_read_b128 v[188:191], v152 offset:64
	ds_read_b128 v[244:247], v152 offset:16704
	s_waitcnt vmcnt(51)
	s_waitcnt lgkmcnt(2)
	v_mfma_f32_16x16x32_bf16 v[228:231], v[0:3], v[180:183], v[228:231]
	v_mfma_f32_16x16x32_bf16 v[232:235], v[0:3], v[184:187], v[232:235]
	global_load_dwordx4 v[0:3], v[166:167], off offset:2816
	ds_read_b128 v[180:183], v152 offset:128
	ds_read_b128 v[184:187], v152 offset:16768
	s_waitcnt vmcnt(51)
	s_waitcnt lgkmcnt(2)
	v_mfma_f32_16x16x32_bf16 v[228:231], v[4:7], v[188:191], v[228:231]
	v_mfma_f32_16x16x32_bf16 v[232:235], v[4:7], v[244:247], v[232:235]
	global_load_dwordx4 v[4:7], v[166:167], off offset:2880
	ds_read_b128 v[188:191], v152 offset:192
	ds_read_b128 v[244:247], v152 offset:16832
	s_waitcnt vmcnt(51)
	s_waitcnt lgkmcnt(2)
	v_mfma_f32_16x16x32_bf16 v[228:231], v[8:11], v[180:183], v[228:231]
	v_mfma_f32_16x16x32_bf16 v[232:235], v[8:11], v[184:187], v[232:235]
	global_load_dwordx4 v[8:11], v[166:167], off offset:2944
	ds_read_b128 v[180:183], v152 offset:256
	ds_read_b128 v[184:187], v152 offset:16896
	s_waitcnt vmcnt(51)
	s_waitcnt lgkmcnt(2)
	v_mfma_f32_16x16x32_bf16 v[228:231], v[12:15], v[188:191], v[228:231]
	v_mfma_f32_16x16x32_bf16 v[232:235], v[12:15], v[244:247], v[232:235]
	global_load_dwordx4 v[12:15], v[166:167], off offset:3008
	ds_read_b128 v[188:191], v152 offset:320
	ds_read_b128 v[244:247], v152 offset:16960
	s_waitcnt vmcnt(51)
	s_waitcnt lgkmcnt(2)
	v_mfma_f32_16x16x32_bf16 v[228:231], v[16:19], v[180:183], v[228:231]
	v_mfma_f32_16x16x32_bf16 v[232:235], v[16:19], v[184:187], v[232:235]
	global_load_dwordx4 v[16:19], v[166:167], off offset:3072
	ds_read_b128 v[180:183], v152 offset:384
	ds_read_b128 v[184:187], v152 offset:17024
	s_waitcnt vmcnt(51)
	s_waitcnt lgkmcnt(2)
	v_mfma_f32_16x16x32_bf16 v[228:231], v[20:23], v[188:191], v[228:231]
	v_mfma_f32_16x16x32_bf16 v[232:235], v[20:23], v[244:247], v[232:235]
	global_load_dwordx4 v[20:23], v[166:167], off offset:3136
	ds_read_b128 v[188:191], v152 offset:448
	ds_read_b128 v[244:247], v152 offset:17088
	s_waitcnt vmcnt(51)
	s_waitcnt lgkmcnt(2)
	v_mfma_f32_16x16x32_bf16 v[228:231], v[24:27], v[180:183], v[228:231]
	v_mfma_f32_16x16x32_bf16 v[232:235], v[24:27], v[184:187], v[232:235]
	global_load_dwordx4 v[24:27], v[166:167], off offset:3200
	ds_read_b128 v[180:183], v152 offset:512
	ds_read_b128 v[184:187], v152 offset:17152
	s_waitcnt vmcnt(51)
	s_waitcnt lgkmcnt(2)
	v_mfma_f32_16x16x32_bf16 v[228:231], v[28:31], v[188:191], v[228:231]
	v_mfma_f32_16x16x32_bf16 v[232:235], v[28:31], v[244:247], v[232:235]
	global_load_dwordx4 v[28:31], v[166:167], off offset:3264
	ds_read_b128 v[188:191], v152 offset:576
	ds_read_b128 v[244:247], v152 offset:17216
	s_waitcnt vmcnt(51)
	s_waitcnt lgkmcnt(2)
	v_mfma_f32_16x16x32_bf16 v[228:231], v[32:35], v[180:183], v[228:231]
	v_mfma_f32_16x16x32_bf16 v[232:235], v[32:35], v[184:187], v[232:235]
	global_load_dwordx4 v[32:35], v[166:167], off offset:3328
	ds_read_b128 v[180:183], v152 offset:640
	ds_read_b128 v[184:187], v152 offset:17280
	s_waitcnt vmcnt(51)
	s_waitcnt lgkmcnt(2)
	v_mfma_f32_16x16x32_bf16 v[228:231], v[36:39], v[188:191], v[228:231]
	v_mfma_f32_16x16x32_bf16 v[232:235], v[36:39], v[244:247], v[232:235]
	global_load_dwordx4 v[36:39], v[166:167], off offset:3392
	ds_read_b128 v[188:191], v152 offset:704
	ds_read_b128 v[244:247], v152 offset:17344
	s_waitcnt vmcnt(51)
	s_waitcnt lgkmcnt(2)
	v_mfma_f32_16x16x32_bf16 v[228:231], v[40:43], v[180:183], v[228:231]
	v_mfma_f32_16x16x32_bf16 v[232:235], v[40:43], v[184:187], v[232:235]
	global_load_dwordx4 v[40:43], v[166:167], off offset:3456
	ds_read_b128 v[180:183], v152 offset:768
	ds_read_b128 v[184:187], v152 offset:17408
	s_waitcnt vmcnt(51)
	s_waitcnt lgkmcnt(2)
	v_mfma_f32_16x16x32_bf16 v[228:231], v[44:47], v[188:191], v[228:231]
	v_mfma_f32_16x16x32_bf16 v[232:235], v[44:47], v[244:247], v[232:235]
	global_load_dwordx4 v[44:47], v[166:167], off offset:3520
	ds_read_b128 v[188:191], v152 offset:832
	ds_read_b128 v[244:247], v152 offset:17472
	s_waitcnt vmcnt(51)
	s_waitcnt lgkmcnt(2)
	v_mfma_f32_16x16x32_bf16 v[228:231], v[48:51], v[180:183], v[228:231]
	v_mfma_f32_16x16x32_bf16 v[232:235], v[48:51], v[184:187], v[232:235]
	global_load_dwordx4 v[48:51], v[166:167], off offset:3584
	ds_read_b128 v[180:183], v152 offset:896
	ds_read_b128 v[184:187], v152 offset:17536
	s_waitcnt vmcnt(51)
	s_waitcnt lgkmcnt(2)
	v_mfma_f32_16x16x32_bf16 v[228:231], v[52:55], v[188:191], v[228:231]
	v_mfma_f32_16x16x32_bf16 v[232:235], v[52:55], v[244:247], v[232:235]
	global_load_dwordx4 v[52:55], v[166:167], off offset:3648
	ds_read_b128 v[188:191], v152 offset:960
	ds_read_b128 v[244:247], v152 offset:17600
	s_waitcnt vmcnt(51)
	s_waitcnt lgkmcnt(2)
	v_mfma_f32_16x16x32_bf16 v[228:231], v[56:59], v[180:183], v[228:231]
	v_mfma_f32_16x16x32_bf16 v[232:235], v[56:59], v[184:187], v[232:235]
	global_load_dwordx4 v[56:59], v[166:167], off offset:3712
	s_waitcnt vmcnt(51)
	s_waitcnt lgkmcnt(0)
	v_mfma_f32_16x16x32_bf16 v[228:231], v[60:63], v[188:191], v[228:231]
	v_mfma_f32_16x16x32_bf16 v[232:235], v[60:63], v[244:247], v[232:235]
	global_load_dwordx4 v[60:63], v[166:167], off offset:3776
	s_waitcnt lgkmcnt(0)
	s_barrier
	s_mov_b64 s[4:5], 0xc00
	s_add_i32 m0, s10, 0x0
	v_lshl_add_u64 v[236:237], v[178:179], 0, s[4:5]
	global_load_lds_dwordx4 v[236:237], off
	s_mov_b64 s[4:5], 0x8c00
	s_add_i32 m0, s10, 0x2080
	v_lshl_add_u64 v[236:237], v[178:179], 0, s[4:5]
	global_load_lds_dwordx4 v[236:237], off
	s_mov_b64 s[4:5], 0x10c00
	s_add_i32 m0, s10, 0x4100
	v_lshl_add_u64 v[236:237], v[178:179], 0, s[4:5]
	global_load_lds_dwordx4 v[236:237], off
	s_mov_b64 s[4:5], 0x18c00
	s_add_i32 m0, s10, 0x6180
	v_lshl_add_u64 v[236:237], v[178:179], 0, s[4:5]
	global_load_lds_dwordx4 v[236:237], off
	s_waitcnt vmcnt(52)
	s_barrier
; #define LBAR() do { asm volatile("s_waitcnt lgkmcnt(0)" ::: "memory"); __builtin_amdgcn_s_barrier(); asm volatile("" ::: "memory"); } while (0)
; #define SG_LA(c, d) do { _Pragma("unroll") for (int ks = 0; ks < 16; ++ks) d[ks] = *(const bf16x8*)(ap + (c) * CK + ks * 32); } while (0)
; #define SG_LB(c) do { _Pragma("unroll") for (int i = 0; i < 4; ++i) sb[i] = *(const u32x4*)(bp + (size_t)(8 * i) * DM + (c) * CK); } while (0)
; #define SG_SB(bufp) do { _Pragma("unroll") for (int i = 0; i < 4; ++i) *(LAS u32x4*)((bufp) + bw + (unsigned)(8 * i * BS * 2)) = sb[i]; } while (0)
; __device__ __forceinline__ void sample_gemm32(LAS unsigned char* lds, const bf16_t* A, const bf16_t* Bt, float* out, int ldo, int n0, int tid, int lane, int wave) {
;     ...
; #pragma unroll 1
;     for (int c = 0; c < NC; c += 2) {
;         SG_LA(c + 1, fn);
;         SG_MM(fa, c);
;         SG_SB(lds + ((c + 1) & 1) * BUFB);
;         if (c + 2 < NC) SG_LB(c + 2);
;         LBAR();
;         if (c + 2 < NC) SG_LA(c + 2, fa);
;         SG_MM(fn, c + 1);
;         if (c + 2 < NC) SG_SB(lds + ((c + 2) & 1) * BUFB);
;         if (c + 3 < NC) SG_LB(c + 3);
	ds_read_b128 v[180:183], v152 offset:33280
	ds_read_b128 v[184:187], v152 offset:49920
	ds_read_b128 v[188:191], v152 offset:33344
	ds_read_b128 v[244:247], v152 offset:49984
	s_waitcnt vmcnt(51)
	s_waitcnt lgkmcnt(2)
	v_mfma_f32_16x16x32_bf16 v[228:231], v[64:67], v[180:183], v[228:231]
	v_mfma_f32_16x16x32_bf16 v[232:235], v[64:67], v[184:187], v[232:235]
	global_load_dwordx4 v[64:67], v[166:167], off offset:3840
	ds_read_b128 v[180:183], v152 offset:33408
	ds_read_b128 v[184:187], v152 offset:50048
	s_waitcnt vmcnt(51)
	s_waitcnt lgkmcnt(2)
	v_mfma_f32_16x16x32_bf16 v[228:231], v[68:71], v[188:191], v[228:231]
	v_mfma_f32_16x16x32_bf16 v[232:235], v[68:71], v[244:247], v[232:235]
	global_load_dwordx4 v[68:71], v[166:167], off offset:3904
	ds_read_b128 v[188:191], v152 offset:33472
	ds_read_b128 v[244:247], v152 offset:50112
	s_waitcnt vmcnt(51)
	s_waitcnt lgkmcnt(2)
	v_mfma_f32_16x16x32_bf16 v[228:231], v[72:75], v[180:183], v[228:231]
	v_mfma_f32_16x16x32_bf16 v[232:235], v[72:75], v[184:187], v[232:235]
	global_load_dwordx4 v[72:75], v[166:167], off offset:3968
	ds_read_b128 v[180:183], v152 offset:33536
	ds_read_b128 v[184:187], v152 offset:50176
	s_waitcnt vmcnt(51)
	s_waitcnt lgkmcnt(2)
	v_mfma_f32_16x16x32_bf16 v[228:231], v[76:79], v[188:191], v[228:231]
	v_mfma_f32_16x16x32_bf16 v[232:235], v[76:79], v[244:247], v[232:235]
	global_load_dwordx4 v[76:79], v[166:167], off offset:4032
	ds_read_b128 v[188:191], v152 offset:33600
	ds_read_b128 v[244:247], v152 offset:50240
	s_waitcnt vmcnt(51)
	s_waitcnt lgkmcnt(2)
	v_mfma_f32_16x16x32_bf16 v[228:231], v[80:83], v[180:183], v[228:231]
	v_mfma_f32_16x16x32_bf16 v[232:235], v[80:83], v[184:187], v[232:235]
	ds_read_b128 v[180:183], v152 offset:33664
	ds_read_b128 v[184:187], v152 offset:50304
	s_waitcnt vmcnt(50)
	s_waitcnt lgkmcnt(2)
	v_mfma_f32_16x16x32_bf16 v[228:231], v[84:87], v[188:191], v[228:231]
	v_mfma_f32_16x16x32_bf16 v[232:235], v[84:87], v[244:247], v[232:235]
	ds_read_b128 v[188:191], v152 offset:33728
	ds_read_b128 v[244:247], v152 offset:50368
	s_waitcnt vmcnt(49)
	s_waitcnt lgkmcnt(2)
	v_mfma_f32_16x16x32_bf16 v[228:231], v[88:91], v[180:183], v[228:231]
	v_mfma_f32_16x16x32_bf16 v[232:235], v[88:91], v[184:187], v[232:235]
	ds_read_b128 v[180:183], v152 offset:33792
	ds_read_b128 v[184:187], v152 offset:50432
	s_waitcnt vmcnt(48)
	s_waitcnt lgkmcnt(2)
	v_mfma_f32_16x16x32_bf16 v[228:231], v[92:95], v[188:191], v[228:231]
	v_mfma_f32_16x16x32_bf16 v[232:235], v[92:95], v[244:247], v[232:235]
	ds_read_b128 v[188:191], v152 offset:33856
	ds_read_b128 v[244:247], v152 offset:50496
	s_waitcnt vmcnt(47)
	s_waitcnt lgkmcnt(2)
	v_mfma_f32_16x16x32_bf16 v[228:231], v[96:99], v[180:183], v[228:231]
	v_mfma_f32_16x16x32_bf16 v[232:235], v[96:99], v[184:187], v[232:235]
	ds_read_b128 v[180:183], v152 offset:33920
	ds_read_b128 v[184:187], v152 offset:50560
	s_waitcnt vmcnt(46)
	s_waitcnt lgkmcnt(2)
	v_mfma_f32_16x16x32_bf16 v[228:231], v[100:103], v[188:191], v[228:231]
	v_mfma_f32_16x16x32_bf16 v[232:235], v[100:103], v[244:247], v[232:235]
	ds_read_b128 v[188:191], v152 offset:33984
	ds_read_b128 v[244:247], v152 offset:50624
	s_waitcnt vmcnt(45)
	s_waitcnt lgkmcnt(2)
	v_mfma_f32_16x16x32_bf16 v[228:231], v[104:107], v[180:183], v[228:231]
	v_mfma_f32_16x16x32_bf16 v[232:235], v[104:107], v[184:187], v[232:235]
	ds_read_b128 v[180:183], v152 offset:34048
	ds_read_b128 v[184:187], v152 offset:50688
	s_waitcnt vmcnt(44)
	s_waitcnt lgkmcnt(2)
	v_mfma_f32_16x16x32_bf16 v[228:231], v[108:111], v[188:191], v[228:231]
	v_mfma_f32_16x16x32_bf16 v[232:235], v[108:111], v[244:247], v[232:235]
	ds_read_b128 v[188:191], v152 offset:34112
	ds_read_b128 v[244:247], v152 offset:50752
	s_waitcnt vmcnt(43)
	s_waitcnt lgkmcnt(2)
	v_mfma_f32_16x16x32_bf16 v[228:231], v[112:115], v[180:183], v[228:231]
	v_mfma_f32_16x16x32_bf16 v[232:235], v[112:115], v[184:187], v[232:235]
	ds_read_b128 v[180:183], v152 offset:34176
	ds_read_b128 v[184:187], v152 offset:50816
	s_waitcnt vmcnt(42)
	s_waitcnt lgkmcnt(2)
	v_mfma_f32_16x16x32_bf16 v[228:231], v[116:119], v[188:191], v[228:231]
	v_mfma_f32_16x16x32_bf16 v[232:235], v[116:119], v[244:247], v[232:235]
	ds_read_b128 v[188:191], v152 offset:34240
	ds_read_b128 v[244:247], v152 offset:50880
	s_waitcnt vmcnt(41)
	s_waitcnt lgkmcnt(2)
	v_mfma_f32_16x16x32_bf16 v[228:231], v[120:123], v[180:183], v[228:231]
	v_mfma_f32_16x16x32_bf16 v[232:235], v[120:123], v[184:187], v[232:235]
	s_waitcnt vmcnt(40)
	s_waitcnt lgkmcnt(0)
	v_mfma_f32_16x16x32_bf16 v[228:231], v[124:127], v[188:191], v[228:231]
	v_mfma_f32_16x16x32_bf16 v[232:235], v[124:127], v[244:247], v[232:235]
	s_waitcnt vmcnt(36)
	s_barrier
; #define LBAR() do { asm volatile("s_waitcnt lgkmcnt(0)" ::: "memory"); __builtin_amdgcn_s_barrier(); asm volatile("" ::: "memory"); } while (0)
; #define SG_LA(c, d) do { _Pragma("unroll") for (int ks = 0; ks < 16; ++ks) d[ks] = *(const bf16x8*)(ap + (c) * CK + ks * 32); } while (0)
; #define SG_LB(c) do { _Pragma("unroll") for (int i = 0; i < 4; ++i) sb[i] = *(const u32x4*)(bp + (size_t)(8 * i) * DM + (c) * CK); } while (0)
; #define SG_SB(bufp) do { _Pragma("unroll") for (int i = 0; i < 4; ++i) *(LAS u32x4*)((bufp) + bw + (unsigned)(8 * i * BS * 2)) = sb[i]; } while (0)
; __device__ __forceinline__ void sample_gemm32(LAS unsigned char* lds, const bf16_t* A, const bf16_t* Bt, float* out, int ldo, int n0, int tid, int lane, int wave) {
;     ...
; #pragma unroll 1
;     for (int c = 0; c < NC; c += 2) {
;         SG_LA(c + 1, fn);
;         SG_MM(fa, c);
;         SG_SB(lds + ((c + 1) & 1) * BUFB);
;         if (c + 2 < NC) SG_LB(c + 2);
;         LBAR();
;         if (c + 2 < NC) SG_LA(c + 2, fa);
;         SG_MM(fn, c + 1);
;         if (c + 2 < NC) SG_SB(lds + ((c + 2) & 1) * BUFB);
;         if (c + 3 < NC) SG_LB(c + 3);
;         LBAR();
	ds_read_b128 v[180:183], v238 offset:0
	ds_read_b128 v[184:187], v238 offset:16640
	ds_read_b128 v[188:191], v238 offset:64
	ds_read_b128 v[244:247], v238 offset:16704
	s_waitcnt vmcnt(35)
	s_waitcnt lgkmcnt(2)
	v_mfma_f32_16x16x32_bf16 v[228:231], v[128:131], v[180:183], v[228:231]
	v_mfma_f32_16x16x32_bf16 v[232:235], v[128:131], v[184:187], v[232:235]
	ds_read_b128 v[180:183], v238 offset:128
	ds_read_b128 v[184:187], v238 offset:16768
	s_waitcnt vmcnt(34)
	s_waitcnt lgkmcnt(2)
	v_mfma_f32_16x16x32_bf16 v[228:231], v[132:135], v[188:191], v[228:231]
	v_mfma_f32_16x16x32_bf16 v[232:235], v[132:135], v[244:247], v[232:235]
	ds_read_b128 v[188:191], v238 offset:192
	ds_read_b128 v[244:247], v238 offset:16832
	s_waitcnt vmcnt(33)
	s_waitcnt lgkmcnt(2)
	v_mfma_f32_16x16x32_bf16 v[228:231], v[136:139], v[180:183], v[228:231]
	v_mfma_f32_16x16x32_bf16 v[232:235], v[136:139], v[184:187], v[232:235]
	ds_read_b128 v[180:183], v238 offset:256
	ds_read_b128 v[184:187], v238 offset:16896
	s_waitcnt vmcnt(32)
	s_waitcnt lgkmcnt(2)
	v_mfma_f32_16x16x32_bf16 v[228:231], v[140:143], v[188:191], v[228:231]
	v_mfma_f32_16x16x32_bf16 v[232:235], v[140:143], v[244:247], v[232:235]
	ds_read_b128 v[188:191], v238 offset:320
	ds_read_b128 v[244:247], v238 offset:16960
	s_waitcnt vmcnt(31)
	s_waitcnt lgkmcnt(2)
	v_mfma_f32_16x16x32_bf16 v[228:231], v[144:147], v[180:183], v[228:231]
	v_mfma_f32_16x16x32_bf16 v[232:235], v[144:147], v[184:187], v[232:235]
	ds_read_b128 v[180:183], v238 offset:384
	ds_read_b128 v[184:187], v238 offset:17024
	s_waitcnt vmcnt(30)
	s_waitcnt lgkmcnt(2)
	v_mfma_f32_16x16x32_bf16 v[228:231], v[148:151], v[188:191], v[228:231]
	v_mfma_f32_16x16x32_bf16 v[232:235], v[148:151], v[244:247], v[232:235]
	ds_read_b128 v[188:191], v238 offset:448
	ds_read_b128 v[244:247], v238 offset:17088
	s_waitcnt vmcnt(29)
	s_waitcnt lgkmcnt(2)
	v_mfma_f32_16x16x32_bf16 v[228:231], v[204:207], v[180:183], v[228:231]
	v_mfma_f32_16x16x32_bf16 v[232:235], v[204:207], v[184:187], v[232:235]
	ds_read_b128 v[180:183], v238 offset:512
	ds_read_b128 v[184:187], v238 offset:17152
	s_waitcnt vmcnt(28)
	s_waitcnt lgkmcnt(2)
	v_mfma_f32_16x16x32_bf16 v[228:231], v[208:211], v[188:191], v[228:231]
	v_mfma_f32_16x16x32_bf16 v[232:235], v[208:211], v[244:247], v[232:235]
	ds_read_b128 v[188:191], v238 offset:576
	ds_read_b128 v[244:247], v238 offset:17216
	s_waitcnt vmcnt(27)
	s_waitcnt lgkmcnt(2)
	v_mfma_f32_16x16x32_bf16 v[228:231], v[212:215], v[180:183], v[228:231]
	v_mfma_f32_16x16x32_bf16 v[232:235], v[212:215], v[184:187], v[232:235]
	ds_read_b128 v[180:183], v238 offset:640
	ds_read_b128 v[184:187], v238 offset:17280
	s_waitcnt vmcnt(26)
	s_waitcnt lgkmcnt(2)
	v_mfma_f32_16x16x32_bf16 v[228:231], v[216:219], v[188:191], v[228:231]
	v_mfma_f32_16x16x32_bf16 v[232:235], v[216:219], v[244:247], v[232:235]
	ds_read_b128 v[188:191], v238 offset:704
	ds_read_b128 v[244:247], v238 offset:17344
	s_waitcnt vmcnt(25)
	s_waitcnt lgkmcnt(2)
	v_mfma_f32_16x16x32_bf16 v[228:231], v[220:223], v[180:183], v[228:231]
	v_mfma_f32_16x16x32_bf16 v[232:235], v[220:223], v[184:187], v[232:235]
	ds_read_b128 v[180:183], v238 offset:768
	ds_read_b128 v[184:187], v238 offset:17408
	s_waitcnt vmcnt(24)
	s_waitcnt lgkmcnt(2)
	v_mfma_f32_16x16x32_bf16 v[228:231], v[224:227], v[188:191], v[228:231]
	v_mfma_f32_16x16x32_bf16 v[232:235], v[224:227], v[244:247], v[232:235]
	ds_read_b128 v[188:191], v238 offset:832
	ds_read_b128 v[244:247], v238 offset:17472
	s_waitcnt vmcnt(23)
	s_waitcnt lgkmcnt(2)
	v_mfma_f32_16x16x32_bf16 v[228:231], v[0:3], v[180:183], v[228:231]
	v_mfma_f32_16x16x32_bf16 v[232:235], v[0:3], v[184:187], v[232:235]
	ds_read_b128 v[180:183], v238 offset:896
	ds_read_b128 v[184:187], v238 offset:17536
	s_waitcnt vmcnt(22)
	s_waitcnt lgkmcnt(2)
	v_mfma_f32_16x16x32_bf16 v[228:231], v[4:7], v[188:191], v[228:231]
	v_mfma_f32_16x16x32_bf16 v[232:235], v[4:7], v[244:247], v[232:235]
	ds_read_b128 v[188:191], v238 offset:960
	ds_read_b128 v[244:247], v238 offset:17600
	s_waitcnt vmcnt(21)
	s_waitcnt lgkmcnt(2)
	v_mfma_f32_16x16x32_bf16 v[228:231], v[8:11], v[180:183], v[228:231]
	v_mfma_f32_16x16x32_bf16 v[232:235], v[8:11], v[184:187], v[232:235]
	s_waitcnt vmcnt(20)
	s_waitcnt lgkmcnt(0)
	v_mfma_f32_16x16x32_bf16 v[228:231], v[12:15], v[188:191], v[228:231]
	v_mfma_f32_16x16x32_bf16 v[232:235], v[12:15], v[244:247], v[232:235]
	s_waitcnt vmcnt(4)
	s_barrier
; #define LBAR() do { asm volatile("s_waitcnt lgkmcnt(0)" ::: "memory"); __builtin_amdgcn_s_barrier(); asm volatile("" ::: "memory"); } while (0)
; #define SG_LA(c, d) do { _Pragma("unroll") for (int ks = 0; ks < 16; ++ks) d[ks] = *(const bf16x8*)(ap + (c) * CK + ks * 32); } while (0)
; #define SG_LB(c) do { _Pragma("unroll") for (int i = 0; i < 4; ++i) sb[i] = *(const u32x4*)(bp + (size_t)(8 * i) * DM + (c) * CK); } while (0)
; #define SG_SB(bufp) do { _Pragma("unroll") for (int i = 0; i < 4; ++i) *(LAS u32x4*)((bufp) + bw + (unsigned)(8 * i * BS * 2)) = sb[i]; } while (0)
; __device__ __forceinline__ void sample_gemm32(LAS unsigned char* lds, const bf16_t* A, const bf16_t* Bt, float* out, int ldo, int n0, int tid, int lane, int wave) {
;     ...
; #pragma unroll 1
;     for (int c = 0; c < NC; c += 2) {
;         SG_LA(c + 1, fn);
;         SG_MM(fa, c);
;         SG_SB(lds + ((c + 1) & 1) * BUFB);
;         if (c + 2 < NC) SG_LB(c + 2);
;         LBAR();
;         if (c + 2 < NC) SG_LA(c + 2, fa);
;         SG_MM(fn, c + 1);
;         if (c + 2 < NC) SG_SB(lds + ((c + 2) & 1) * BUFB);
;         if (c + 3 < NC) SG_LB(c + 3);
;         LBAR();
;     }
;     ...
; #pragma unroll
;     for (int nt = 0; nt < 2; ++nt)
; #pragma unroll
;         for (int j = 0; j < 4; ++j) out[(size_t)(wave * 16 + q8 * 4 + j) * ldo + n0 + nt * 16 + r] = acc[nt][j];
	ds_read_b128 v[180:183], v152 offset:0
	ds_read_b128 v[184:187], v152 offset:16640
	ds_read_b128 v[188:191], v152 offset:64
	ds_read_b128 v[244:247], v152 offset:16704
	s_waitcnt vmcnt(19)
	s_waitcnt lgkmcnt(2)
	v_mfma_f32_16x16x32_bf16 v[228:231], v[16:19], v[180:183], v[228:231]
	v_mfma_f32_16x16x32_bf16 v[232:235], v[16:19], v[184:187], v[232:235]
	ds_read_b128 v[180:183], v152 offset:128
	ds_read_b128 v[184:187], v152 offset:16768
	s_waitcnt vmcnt(18)
	s_waitcnt lgkmcnt(2)
	v_mfma_f32_16x16x32_bf16 v[228:231], v[20:23], v[188:191], v[228:231]
	v_mfma_f32_16x16x32_bf16 v[232:235], v[20:23], v[244:247], v[232:235]
	ds_read_b128 v[188:191], v152 offset:192
	ds_read_b128 v[244:247], v152 offset:16832
	s_waitcnt vmcnt(17)
	s_waitcnt lgkmcnt(2)
	v_mfma_f32_16x16x32_bf16 v[228:231], v[24:27], v[180:183], v[228:231]
	v_mfma_f32_16x16x32_bf16 v[232:235], v[24:27], v[184:187], v[232:235]
	ds_read_b128 v[180:183], v152 offset:256
	ds_read_b128 v[184:187], v152 offset:16896
	s_waitcnt vmcnt(16)
	s_waitcnt lgkmcnt(2)
	v_mfma_f32_16x16x32_bf16 v[228:231], v[28:31], v[188:191], v[228:231]
	v_mfma_f32_16x16x32_bf16 v[232:235], v[28:31], v[244:247], v[232:235]
	ds_read_b128 v[188:191], v152 offset:320
	ds_read_b128 v[244:247], v152 offset:16960
	s_waitcnt vmcnt(15)
	s_waitcnt lgkmcnt(2)
	v_mfma_f32_16x16x32_bf16 v[228:231], v[32:35], v[180:183], v[228:231]
	v_mfma_f32_16x16x32_bf16 v[232:235], v[32:35], v[184:187], v[232:235]
	ds_read_b128 v[180:183], v152 offset:384
	ds_read_b128 v[184:187], v152 offset:17024
	s_waitcnt vmcnt(14)
	s_waitcnt lgkmcnt(2)
	v_mfma_f32_16x16x32_bf16 v[228:231], v[36:39], v[188:191], v[228:231]
	v_mfma_f32_16x16x32_bf16 v[232:235], v[36:39], v[244:247], v[232:235]
	ds_read_b128 v[188:191], v152 offset:448
	ds_read_b128 v[244:247], v152 offset:17088
	s_waitcnt vmcnt(13)
	s_waitcnt lgkmcnt(2)
	v_mfma_f32_16x16x32_bf16 v[228:231], v[40:43], v[180:183], v[228:231]
	v_mfma_f32_16x16x32_bf16 v[232:235], v[40:43], v[184:187], v[232:235]
	ds_read_b128 v[180:183], v152 offset:512
	ds_read_b128 v[184:187], v152 offset:17152
	s_waitcnt vmcnt(12)
	s_waitcnt lgkmcnt(2)
	v_mfma_f32_16x16x32_bf16 v[228:231], v[44:47], v[188:191], v[228:231]
	v_mfma_f32_16x16x32_bf16 v[232:235], v[44:47], v[244:247], v[232:235]
	ds_read_b128 v[188:191], v152 offset:576
	ds_read_b128 v[244:247], v152 offset:17216
	s_waitcnt vmcnt(11)
	s_waitcnt lgkmcnt(2)
	v_mfma_f32_16x16x32_bf16 v[228:231], v[48:51], v[180:183], v[228:231]
	v_mfma_f32_16x16x32_bf16 v[232:235], v[48:51], v[184:187], v[232:235]
	ds_read_b128 v[180:183], v152 offset:640
	ds_read_b128 v[184:187], v152 offset:17280
	s_waitcnt vmcnt(10)
	s_waitcnt lgkmcnt(2)
	v_mfma_f32_16x16x32_bf16 v[228:231], v[52:55], v[188:191], v[228:231]
	v_mfma_f32_16x16x32_bf16 v[232:235], v[52:55], v[244:247], v[232:235]
	ds_read_b128 v[188:191], v152 offset:704
	ds_read_b128 v[244:247], v152 offset:17344
	s_waitcnt vmcnt(9)
	s_waitcnt lgkmcnt(2)
	v_mfma_f32_16x16x32_bf16 v[228:231], v[56:59], v[180:183], v[228:231]
	v_mfma_f32_16x16x32_bf16 v[232:235], v[56:59], v[184:187], v[232:235]
	ds_read_b128 v[180:183], v152 offset:768
	ds_read_b128 v[184:187], v152 offset:17408
	s_waitcnt vmcnt(8)
	s_waitcnt lgkmcnt(2)
	v_mfma_f32_16x16x32_bf16 v[228:231], v[60:63], v[188:191], v[228:231]
	v_mfma_f32_16x16x32_bf16 v[232:235], v[60:63], v[244:247], v[232:235]
	ds_read_b128 v[188:191], v152 offset:832
	ds_read_b128 v[244:247], v152 offset:17472
	s_waitcnt vmcnt(3)
	s_waitcnt lgkmcnt(2)
	v_mfma_f32_16x16x32_bf16 v[228:231], v[64:67], v[180:183], v[228:231]
	v_mfma_f32_16x16x32_bf16 v[232:235], v[64:67], v[184:187], v[232:235]
	ds_read_b128 v[180:183], v152 offset:896
	ds_read_b128 v[184:187], v152 offset:17536
	s_waitcnt vmcnt(2)
	s_waitcnt lgkmcnt(2)
	v_mfma_f32_16x16x32_bf16 v[228:231], v[68:71], v[188:191], v[228:231]
	v_mfma_f32_16x16x32_bf16 v[232:235], v[68:71], v[244:247], v[232:235]
	ds_read_b128 v[188:191], v152 offset:960
	ds_read_b128 v[244:247], v152 offset:17600
	s_waitcnt vmcnt(1)
	s_waitcnt lgkmcnt(2)
	v_mfma_f32_16x16x32_bf16 v[228:231], v[72:75], v[180:183], v[228:231]
	v_mfma_f32_16x16x32_bf16 v[232:235], v[72:75], v[184:187], v[232:235]
	s_waitcnt vmcnt(0)
	s_waitcnt lgkmcnt(0)
	v_mfma_f32_16x16x32_bf16 v[228:231], v[76:79], v[188:191], v[228:231]
	v_mfma_f32_16x16x32_bf16 v[232:235], v[76:79], v[244:247], v[232:235]
	s_nop 7
	v_mov_b32_e32 v84, v228
	v_mov_b32_e32 v85, v229
	v_mov_b32_e32 v86, v230
	v_mov_b32_e32 v87, v231
	v_mov_b32_e32 v80, v232
	v_mov_b32_e32 v81, v233
	v_mov_b32_e32 v82, v234
	v_mov_b32_e32 v83, v235
	s_branch .LBB0_349
